# retention scores loop: counted waits of the staging loads no longer include the previous unit's eight result stores (hipcc had merged the loop-entry count into the back-edge path)
# speedup vs baseline: 1.0030x; 1.0030x over previous
.LBB0_550:
	s_or_b64 exec, exec, s[4:5]
	s_mov_b64 s[12:13], s[0:1]
	s_and_b32 s8, s2, 7
	s_lshl_b32 s8, s8, 8
	s_lshr_b32 s9, s2, 3
	s_or_b32 s8, s8, s9
	s_waitcnt lgkmcnt(0)
	s_barrier
	v_mbcnt_lo_u32_b32 v44, -1, 0
	v_mbcnt_hi_u32_b32 v44, -1, v44
	s_cmpk_gt_i32 s8, 0x7ff
	v_add_u32_e32 v0, s33, v44
	s_nop 0
	v_readfirstlane_b32 s9, v0
	s_cbranch_scc1 .LBB0_558
	s_load_dwordx4 s[4:7], s[12:13], 0x98
	v_add_u32_e32 v1, 0x200, v0
	v_ashrrev_i32_e32 v32, 5, v0
	v_ashrrev_i32_e32 v34, 5, v1
	v_add_u32_e32 v1, 0x400, v0
	s_waitcnt lgkmcnt(0)
	s_add_u32 s12, s6, 0x8800000
	s_addc_u32 s13, s7, 0
	s_add_u32 s14, s6, 0x4800000
	s_addc_u32 s15, s7, 0
	s_lshl_b32 s6, s8, 3
	v_add_u32_e32 v0, 0x600, v0
	s_and_b32 s6, s6, 0x600
	v_ashrrev_i32_e32 v38, 5, v0
	s_add_u32 s16, s12, s6
	v_lshlrev_b32_e32 v0, 4, v44
	s_addc_u32 s17, s13, 0
	v_and_b32_e32 v42, 0x1f0, v0
	v_mov_b32_e32 v43, 0
	v_lshl_add_u64 v[8:9], s[16:17], 0, v[42:43]
	s_ashr_i32 s16, s8, 8
	s_ashr_i32 s17, s16, 31
	s_lshl_b32 s18, s8, 6
	s_lshl_b64 s[16:17], s[16:17], 12
	s_and_b32 s18, s18, 0xfc0
	v_ashrrev_i32_e32 v33, 31, v32
	s_or_b32 s16, s16, s18
	v_ashrrev_i32_e32 v35, 31, v34
	v_ashrrev_i32_e32 v36, 5, v1
	v_lshl_add_u64 v[0:1], s[16:17], 0, v[32:33]
	v_lshlrev_b64 v[16:17], 11, v[0:1]
	v_lshl_add_u64 v[0:1], s[16:17], 0, v[34:35]
	v_ashrrev_i32_e32 v37, 31, v36
	v_lshl_add_u64 v[10:11], v[8:9], 0, v[16:17]
	v_lshlrev_b64 v[18:19], 11, v[0:1]
	v_ashrrev_i32_e32 v39, 31, v38
	v_lshl_add_u64 v[12:13], v[8:9], 0, v[18:19]
	global_load_dwordx4 v[4:7], v[10:11], off
	global_load_dwordx4 v[0:3], v[12:13], off
	v_lshl_add_u64 v[10:11], s[16:17], 0, v[36:37]
	v_lshlrev_b64 v[24:25], 11, v[10:11]
	v_lshl_add_u64 v[10:11], s[16:17], 0, v[38:39]
	s_add_u32 s16, s14, s6
	s_addc_u32 s17, s15, 0
	v_lshlrev_b64 v[26:27], 11, v[10:11]
	v_lshl_add_u64 v[28:29], s[16:17], 0, v[42:43]
	v_lshl_add_u64 v[20:21], v[8:9], 0, v[24:25]
	v_lshl_add_u64 v[22:23], v[8:9], 0, v[26:27]
	v_lshl_add_u64 v[30:31], v[28:29], 0, v[16:17]
	v_lshl_add_u64 v[40:41], v[28:29], 0, v[18:19]
	global_load_dwordx4 v[8:11], v[20:21], off
	global_load_dwordx4 v[12:15], v[22:23], off
	s_nop 0
	global_load_dwordx4 v[20:23], v[30:31], off
	global_load_dwordx4 v[16:19], v[40:41], off
	v_lshl_add_u64 v[40:41], v[28:29], 0, v[24:25]
	v_lshl_add_u64 v[46:47], v[28:29], 0, v[26:27]
	global_load_dwordx4 v[24:27], v[40:41], off
	global_load_dwordx4 v[28:31], v[46:47], off
	s_ashr_i32 s6, s9, 3
	v_and_b32_e32 v45, 15, v44
	v_bfe_u32 v52, v44, 4, 2
	v_add_u32_e32 v72, 0, v42
	v_lshl_add_u64 v[40:41], s[14:15], 0, v[42:43]
	v_lshl_add_u64 v[42:43], s[12:13], 0, v[42:43]
	v_bfi_b32 v44, -16, s6, v44
	s_movk_i32 s13, 0x210
	s_and_b32 s12, s6, -16
	v_mul_lo_u32 v44, v44, s13
	s_lshr_b32 s9, s9, 1
	v_add_u32_e32 v73, 0, v44
	v_and_or_b32 v53, s9, 32, v45
	v_lshl_or_b32 v44, v52, 2, s12
	v_or_b32_e32 v45, 16, v53
	v_sub_u32_e32 v46, v53, v44
	v_not_b32_e32 v60, 63
	v_lshl_add_u32 v46, v46, 1, v60
	v_sub_u32_e32 v48, v45, v44
	v_cvt_f32_i32_e32 v46, v46
	v_lshl_add_u32 v48, v48, 1, v60
	v_cvt_f32_i32_e32 v48, v48
	v_mov_b32_e32 v47, 0xc2800000
	v_cmp_gt_i32_e32 vcc, v53, v44
	s_ashr_i32 s9, s8, 31
	v_mad_u32_u24 v75, v53, s13, 0
	v_cndmask_b32_e32 v61, v47, v46, vcc
	v_cmp_gt_i32_e32 vcc, v45, v44
	v_or_b32_e32 v46, 1, v44
	v_sub_u32_e32 v49, v45, v46
	v_cndmask_b32_e32 v62, v47, v48, vcc
	v_sub_u32_e32 v48, v53, v46
	v_lshl_add_u32 v48, v48, 1, v60
	v_cvt_f32_i32_e32 v48, v48
	v_lshl_add_u32 v49, v49, 1, v60
	v_cmp_gt_i32_e32 vcc, v53, v46
	v_cvt_f32_i32_e32 v49, v49
	v_mul_lo_u32 v69, v32, s13
	v_cndmask_b32_e32 v63, v47, v48, vcc
	v_cmp_gt_i32_e32 vcc, v45, v46
	v_or_b32_e32 v46, 2, v44
	v_sub_u32_e32 v48, v53, v46
	v_lshl_add_u32 v48, v48, 1, v60
	v_cvt_f32_i32_e32 v48, v48
	v_cndmask_b32_e32 v64, v47, v49, vcc
	v_sub_u32_e32 v49, v45, v46
	v_lshl_add_u32 v49, v49, 1, v60
	v_cvt_f32_i32_e32 v49, v49
	v_cmp_gt_i32_e32 vcc, v53, v46
	v_mul_lo_u32 v77, v34, s13
	v_mul_lo_u32 v78, v36, s13
	v_cndmask_b32_e32 v65, v47, v48, vcc
	v_cmp_gt_i32_e32 vcc, v45, v46
	v_or_b32_e32 v46, 3, v44
	v_sub_u32_e32 v48, v53, v46
	v_lshl_add_u32 v48, v48, 1, v60
	v_cndmask_b32_e32 v66, v47, v49, vcc
	v_cvt_f32_i32_e32 v48, v48
	v_sub_u32_e32 v49, v45, v46
	v_mul_lo_u32 v79, v38, s13
	v_lshl_add_u32 v49, v49, 1, v60
	s_lshl_b64 s[12:13], s[8:9], 13
	v_cvt_f32_i32_e32 v49, v49
	s_add_u32 s4, s4, s12
	v_cmp_gt_i32_e32 vcc, v53, v46
	s_addc_u32 s5, s5, s13
	s_lshl_b32 s6, s6, 6
	v_cndmask_b32_e32 v67, v47, v48, vcc
	v_lshlrev_b32_e32 v48, 6, v44
	s_and_b32 s6, s6, 0xfffffc00
	v_lshlrev_b32_e32 v74, 4, v52
	v_lshlrev_b32_e32 v76, 3, v52
	v_cmp_gt_i32_e32 vcc, v45, v46
	v_or_b32_e32 v44, 0xc0, v48
	v_or_b32_e32 v46, 0x80, v48
	v_or_b32_e32 v48, 64, v48
	v_lshl_or_b32 v52, v52, 8, s6
	v_cndmask_b32_e32 v68, v47, v49, vcc
	v_ashrrev_i32_e32 v45, 31, v44
	v_or_b32_e32 v44, v44, v53
	v_mov_b64_e32 v[50:51], 0x4000020
	v_ashrrev_i32_e32 v47, 31, v46
	v_or_b32_e32 v46, v46, v53
	v_ashrrev_i32_e32 v49, 31, v48
	v_or_b32_e32 v48, v48, v53
	v_ashrrev_i32_e32 v59, 31, v52
	v_or_b32_e32 v58, v52, v53
	v_lshl_add_u64 v[44:45], v[44:45], 1, v[50:51]
	v_lshl_add_u64 v[46:47], v[46:47], 1, v[50:51]
	v_lshl_add_u64 v[48:49], v[48:49], 1, v[50:51]
	v_lshl_add_u64 v[50:51], v[58:59], 1, v[50:51]
	v_ashrrev_i32_e32 v59, 31, v58
	v_mov_b64_e32 v[70:71], 0x4000000
	v_lshl_add_u64 v[52:53], v[58:59], 1, v[70:71]
	v_or_b32_e32 v54, 64, v58
	v_or_b32_e32 v56, 0x80, v58
	v_or_b32_e32 v58, 0xc0, v58
	v_ashrrev_i32_e32 v55, 31, v54
	v_ashrrev_i32_e32 v57, 31, v56
	v_ashrrev_i32_e32 v59, 31, v58
	s_mov_b32 s7, 0
	v_lshl_add_u64 v[54:55], v[54:55], 1, v[70:71]
	v_lshl_add_u64 v[56:57], v[56:57], 1, v[70:71]
	v_lshl_add_u64 v[58:59], v[58:59], 1, v[70:71]
	v_add_u32_e32 v69, v72, v69
	v_add_u32_e32 v70, v72, v77
	v_add_u32_e32 v71, v72, v78
	v_add_u32_e32 v72, v72, v79
	v_add_u32_e32 v73, v73, v74
	v_add_u32_e32 v74, v75, v76
	s_mov_b32 s9, 0xc2fc0000
	s_movk_i32 s16, 0x7fff
	v_mov_b32_e32 v75, 0xbbb906ce
	v_mov_b32_e32 v76, 0xbc3963dd
	v_mov_b32_e32 v77, 0x42800000
	s_waitcnt vmcnt(0)
	s_branch .LBB0_554

.LBB0_554:
	s_mov_b32 s14, s8
	s_addk_i32 s8, 0x20
	s_and_b32 s15, s14, 0xff
	s_cmpk_gt_i32 s15, 0xdf
	s_cselect_b64 s[12:13], -1, 0
	s_cmpk_lt_i32 s15, 0xe0
	s_cselect_b32 s6, s8, 0x7ff
	s_ashr_i32 s18, s6, 8
	s_ashr_i32 s19, s18, 31
	s_lshl_b32 s15, s6, 6
	s_lshl_b64 s[18:19], s[18:19], 12
	s_and_b32 s15, s15, 0xfc0
	s_or_b32 s18, s18, s15
	s_lshl_b32 s6, s6, 3
	s_waitcnt vmcnt(63) expcnt(7) lgkmcnt(15)
	s_barrier
	s_waitcnt vmcnt(14)
	ds_write_b128 v69, v[20:23]
	ds_write_b128 v69, v[4:7] offset:33792
	s_waitcnt vmcnt(12)
	ds_write_b128 v70, v[16:19]
	ds_write_b128 v70, v[0:3] offset:33792
	s_waitcnt vmcnt(10)
	ds_write_b128 v71, v[24:27]
	ds_write_b128 v71, v[8:11] offset:33792
	s_waitcnt vmcnt(8)
	ds_write_b128 v72, v[28:31]
	ds_write_b128 v72, v[12:15] offset:33792
	s_and_b32 s6, s6, 0x600
	v_lshl_add_u64 v[0:1], s[18:19], 0, v[32:33]
	v_lshl_add_u64 v[12:13], v[40:41], 0, s[6:7]
	v_lshl_add_u64 v[14:15], v[42:43], 0, s[6:7]
	v_lshlrev_b64 v[0:1], 11, v[0:1]
	v_lshl_add_u64 v[2:3], v[12:13], 0, v[0:1]
	v_lshl_add_u64 v[0:1], v[14:15], 0, v[0:1]
	global_load_dwordx4 v[20:23], v[2:3], off
	global_load_dwordx4 v[4:7], v[0:1], off
	v_lshl_add_u64 v[0:1], s[18:19], 0, v[34:35]
	v_lshlrev_b64 v[0:1], 11, v[0:1]
	v_lshl_add_u64 v[8:9], v[12:13], 0, v[0:1]
	v_lshl_add_u64 v[10:11], v[14:15], 0, v[0:1]
	global_load_dwordx4 v[16:19], v[8:9], off
	global_load_dwordx4 v[0:3], v[10:11], off
	v_lshl_add_u64 v[8:9], s[18:19], 0, v[36:37]
	v_lshlrev_b64 v[8:9], 11, v[8:9]
	v_lshl_add_u64 v[28:29], v[12:13], 0, v[8:9]
	v_lshl_add_u64 v[30:31], v[14:15], 0, v[8:9]
	global_load_dwordx4 v[24:27], v[28:29], off
	global_load_dwordx4 v[8:11], v[30:31], off
	v_lshl_add_u64 v[28:29], s[18:19], 0, v[38:39]
	v_lshlrev_b64 v[28:29], 11, v[28:29]
	v_lshl_add_u64 v[78:79], v[12:13], 0, v[28:29]
	v_lshl_add_u64 v[80:81], v[14:15], 0, v[28:29]
	global_load_dwordx4 v[28:31], v[78:79], off
	global_load_dwordx4 v[12:15], v[80:81], off
	s_bfe_u32 s6, s14, 0x20006
	s_cmp_lt_i32 s6, 1
	v_mov_b32_e32 v78, 0xbd3b9ca6
	s_waitcnt lgkmcnt(0)
	s_barrier
	s_cbranch_scc1 .LBB0_553
	s_cmp_eq_u32 s6, 1
	s_cbranch_scc1 .LBB0_557
	s_cmp_eq_u32 s6, 2
	s_cselect_b64 vcc, -1, 0
	v_cndmask_b32_e32 v78, v75, v76, vcc
	s_cbranch_execnz .LBB0_553
	s_branch .LBB0_552
